# same as previous + a generic path at every converted barrier site for grids other than 256 workgroups (flat full-fence grid barrier); verified by a forced run
# speedup vs baseline: 1.0062x; 1.0012x over previous
; __device__ __forceinline__ unsigned xb_ld(unsigned* p)              { return __hip_atomic_load(p, __ATOMIC_RELAXED, __HIP_MEMORY_SCOPE_AGENT); }
; __device__ __forceinline__ unsigned xb_add(unsigned* p, unsigned v) { return __hip_atomic_fetch_add(p, v, __ATOMIC_RELAXED, __HIP_MEMORY_SCOPE_AGENT); }
; #define XB_SPIN(cond, bar) do { unsigned _sp = 0; while (cond) { __builtin_amdgcn_s_sleep(1); \
;     if ((++_sp & 255u) == 0u) { if (xb_ld(&(bar)[XB_TMO])) break; if (_sp > XB_SPIN_CAP) { atomicAdd(&(bar)[XB_TMO], 1u); break; } } } } while (0)
; __device__ __forceinline__ void xcd_barrier(const XcdBarrier& b) {
;     asm volatile("s_waitcnt vmcnt(0)" ::: "memory");
;     __syncthreads();
;     if (threadIdx.x == 0) {
;         unsigned* bar = b.bar;
;         __builtin_amdgcn_s_waitcnt(0);
;         unsigned nloc = b.st[0], nx = b.st[1];
;         if (nloc == 0u) { xcd_barrier_complete(bar, b.x, nloc, nx); b.st[0] = nloc; b.st[1] = nx; }
;         const unsigned old = xb_add(&bar[XB_XSUB(b.x)], 1u);
;         const unsigned gen = old / nloc;
;         if (old + 1u == (gen + 1u) * nloc) {
;             __builtin_amdgcn_fence(__ATOMIC_RELEASE, "agent");
;             asm volatile("s_waitcnt vmcnt(0)" ::: "memory");
;             const unsigned og = xb_add(&bar[XB_TOP], 1u);
;             const unsigned tg = og / nx;
;             if (og + 1u == (tg + 1u) * nx) xb_add(&bar[XB_TOPGEN], 1u);
;             else XB_SPIN(xb_ld(&bar[XB_TOPGEN]) == tg, bar);
;             __builtin_amdgcn_fence(__ATOMIC_ACQUIRE, "agent");
;             xb_add(&bar[XB_XGEN(b.x)], 1u);
;             asm volatile("s_waitcnt vmcnt(0)" ::: "memory");
;         } else {
;             XB_SPIN(xb_ld(&bar[XB_XGEN(b.x)]) == gen, bar);
;             __builtin_amdgcn_fence(__ATOMIC_ACQUIRE, "agent");
;             asm volatile("s_waitcnt vmcnt(0)" ::: "memory");
;         }
;     }
;     __syncthreads();
; }
.LBB0_322:
	s_waitcnt vmcnt(0)
	s_waitcnt vmcnt(0) lgkmcnt(0)
	s_barrier
	s_mov_b64 s[0:1], exec
	v_readlane_b32 s2, v247, 37
	v_readlane_b32 s3, v247, 38
	s_and_b64 s[2:3], s[0:1], s[2:3]
	s_mov_b64 exec, s[2:3]
	s_cbranch_execz .LBB0_374
	s_cmpk_eq_i32 s80, 0x100
	s_cbranch_scc1 .Lgrpbar3_g256
	buffer_wbl2 sc1
	s_add_u32 s2, s62, 0x7b00
	s_addc_u32 s3, s63, 0
	v_mov_b32_e32 v1, 0
	v_mov_b32_e32 v2, 1
	s_mov_b32 s4, 0
	s_waitcnt vmcnt(0) lgkmcnt(0)
	global_atomic_add v1, v2, s[2:3]
.Lgrpbar3_xspin:
	global_load_dword v3, v1, s[2:3] sc1
	s_waitcnt vmcnt(0)
	v_cmp_le_u32_e32 vcc, s80, v3
	s_cbranch_vccnz .Lgrpbar3_xdone
	s_sleep 1
	s_add_i32 s4, s4, 1
	s_cmp_lt_u32 s4, 0x200000
	s_cbranch_scc1 .Lgrpbar3_xspin
.Lgrpbar3_xdone:
	buffer_inv sc1
	s_waitcnt vmcnt(0)
	s_branch .Lgrpbar3_end
.Lgrpbar3_g256:
	v_readlane_b32 s5, v247, 36
	s_and_b32 s2, s90, 31
	s_lshl_b32 s2, s2, 6
	s_add_u32 s6, s62, s2
	s_addc_u32 s7, s63, 0
	s_add_u32 s6, s6, 0xa000
	s_addc_u32 s7, s7, 0
	v_mov_b32_e32 v1, 0
	global_load_dword v3, v1, s[6:7] sc1
	s_and_b32 s2, s90, 7
	s_lshl_b32 s2, s2, 7
	s_lshr_b32 s6, s5, 2
	s_and_b32 s6, s6, 1
	s_lshl_b32 s6, s6, 6
	s_add_i32 s2, s2, s6
	s_add_u32 s6, s62, s2
	s_addc_u32 s7, s63, 0
	s_add_u32 s6, s6, 0xa800
	s_addc_u32 s7, s7, 0
	global_load_dword v2, v1, s[6:7] sc1
	s_and_b32 s6, s5, 7
	s_lshl_b32 s6, s6, 2
	s_lshl_b32 s6, 8, s6
	s_and_b32 s7, s5, 3
	s_lshl_b32 s7, s7, 3
	s_lshl_b32 s7, 32, s7
	s_mov_b32 s4, 0
	s_waitcnt vmcnt(0) lgkmcnt(0)
	v_cmp_eq_u32_e32 vcc, s6, v3
	s_cmp_lg_u64 vcc, 0
	s_cselect_b32 s6, 1, 0
	v_cmp_eq_u32_e32 vcc, s7, v2
	s_cmp_lg_u64 vcc, 0
	s_cselect_b32 s5, 1, 0
	v_writelane_b32 v246, s6, 62
	v_writelane_b32 v246, s5, 63
	v_mov_b32_e32 v2, 1
	s_and_b32 s2, s90, 7
	s_lshl_b32 s2, s2, 7
	s_add_u32 s2, s62, s2
	s_addc_u32 s3, s63, 0
	s_add_u32 s2, s2, 0xe000
	s_addc_u32 s3, s3, 0
	s_add_u32 s6, s62, 0xd000
	s_addc_u32 s7, s63, 0
	s_cmp_eq_u32 s5, 1
	s_cbranch_scc1 .Lgrpbar3_same
	buffer_wbl2 sc1
	s_waitcnt vmcnt(0)

; __device__ __forceinline__ void xcd_barrier(const XcdBarrier& b) {
;     ...
;     __syncthreads();
; }
.Lgrpbar3_noinv:
.Lgrpbar3_end:
.LBB0_374:
	s_or_b64 exec, exec, s[0:1]
	s_waitcnt lgkmcnt(0)
	s_barrier

; __device__ __forceinline__ unsigned xb_ld(unsigned* p)              { return __hip_atomic_load(p, __ATOMIC_RELAXED, __HIP_MEMORY_SCOPE_AGENT); }
; __device__ __forceinline__ unsigned xb_add(unsigned* p, unsigned v) { return __hip_atomic_fetch_add(p, v, __ATOMIC_RELAXED, __HIP_MEMORY_SCOPE_AGENT); }
; #define XB_SPIN(cond, bar) do { unsigned _sp = 0; while (cond) { __builtin_amdgcn_s_sleep(1); \
;     if ((++_sp & 255u) == 0u) { if (xb_ld(&(bar)[XB_TMO])) break; if (_sp > XB_SPIN_CAP) { atomicAdd(&(bar)[XB_TMO], 1u); break; } } } } while (0)
; __device__ __forceinline__ void xcd_barrier(const XcdBarrier& b) {
;     asm volatile("s_waitcnt vmcnt(0)" ::: "memory");
;     __syncthreads();
;     if (threadIdx.x == 0) {
;         unsigned* bar = b.bar;
;         __builtin_amdgcn_s_waitcnt(0);
;         unsigned nloc = b.st[0], nx = b.st[1];
;         if (nloc == 0u) { xcd_barrier_complete(bar, b.x, nloc, nx); b.st[0] = nloc; b.st[1] = nx; }
;         const unsigned old = xb_add(&bar[XB_XSUB(b.x)], 1u);
;         const unsigned gen = old / nloc;
;         if (old + 1u == (gen + 1u) * nloc) {
;             __builtin_amdgcn_fence(__ATOMIC_RELEASE, "agent");
;             asm volatile("s_waitcnt vmcnt(0)" ::: "memory");
;             const unsigned og = xb_add(&bar[XB_TOP], 1u);
;             const unsigned tg = og / nx;
;             if (og + 1u == (tg + 1u) * nx) xb_add(&bar[XB_TOPGEN], 1u);
;             else XB_SPIN(xb_ld(&bar[XB_TOPGEN]) == tg, bar);
;             __builtin_amdgcn_fence(__ATOMIC_ACQUIRE, "agent");
;             xb_add(&bar[XB_XGEN(b.x)], 1u);
;             asm volatile("s_waitcnt vmcnt(0)" ::: "memory");
;         } else {
;             XB_SPIN(xb_ld(&bar[XB_XGEN(b.x)]) == gen, bar);
;             __builtin_amdgcn_fence(__ATOMIC_ACQUIRE, "agent");
;             asm volatile("s_waitcnt vmcnt(0)" ::: "memory");
;         }
;     }
;     __syncthreads();
; }
.LBB0_507:
	v_readlane_b32 s18, v247, 47
	v_readlane_b32 s19, v247, 48
	s_cmp_gt_i32 s19, 4
	s_cbranch_scc0 .LBB0_561
	s_waitcnt vmcnt(0)
	s_waitcnt vmcnt(0) lgkmcnt(0)
	s_barrier
	s_mov_b64 s[0:1], exec
	v_readlane_b32 s2, v247, 37
	v_readlane_b32 s3, v247, 38
	s_and_b64 s[2:3], s[0:1], s[2:3]
	s_mov_b64 exec, s[2:3]
	s_cbranch_execz .LBB0_560
	s_cmpk_eq_i32 s80, 0x100
	s_cbranch_scc1 .Lgrpbar4_g256
	buffer_wbl2 sc1
	s_add_u32 s2, s62, 0x7c00
	s_addc_u32 s3, s63, 0
	v_mov_b32_e32 v1, 0
	v_mov_b32_e32 v2, 1
	s_mov_b32 s4, 0
	s_waitcnt vmcnt(0) lgkmcnt(0)
	global_atomic_add v1, v2, s[2:3]

; __device__ __forceinline__ unsigned xb_ld(unsigned* p)              { return __hip_atomic_load(p, __ATOMIC_RELAXED, __HIP_MEMORY_SCOPE_AGENT); }
; __device__ __forceinline__ unsigned xb_add(unsigned* p, unsigned v) { return __hip_atomic_fetch_add(p, v, __ATOMIC_RELAXED, __HIP_MEMORY_SCOPE_AGENT); }
; #define XB_SPIN(cond, bar) do { unsigned _sp = 0; while (cond) { __builtin_amdgcn_s_sleep(1); \
;     if ((++_sp & 255u) == 0u) { if (xb_ld(&(bar)[XB_TMO])) break; if (_sp > XB_SPIN_CAP) { atomicAdd(&(bar)[XB_TMO], 1u); break; } } } } while (0)
; __device__ __forceinline__ void xcd_barrier(const XcdBarrier& b) {
;     asm volatile("s_waitcnt vmcnt(0)" ::: "memory");
;     __syncthreads();
;     if (threadIdx.x == 0) {
;         unsigned* bar = b.bar;
;         __builtin_amdgcn_s_waitcnt(0);
;         unsigned nloc = b.st[0], nx = b.st[1];
;         if (nloc == 0u) { xcd_barrier_complete(bar, b.x, nloc, nx); b.st[0] = nloc; b.st[1] = nx; }
;         const unsigned old = xb_add(&bar[XB_XSUB(b.x)], 1u);
;         const unsigned gen = old / nloc;
;         if (old + 1u == (gen + 1u) * nloc) {
;             __builtin_amdgcn_fence(__ATOMIC_RELEASE, "agent");
;             asm volatile("s_waitcnt vmcnt(0)" ::: "memory");
;             const unsigned og = xb_add(&bar[XB_TOP], 1u);
;             const unsigned tg = og / nx;
;             if (og + 1u == (tg + 1u) * nx) xb_add(&bar[XB_TOPGEN], 1u);
;             else XB_SPIN(xb_ld(&bar[XB_TOPGEN]) == tg, bar);
;             __builtin_amdgcn_fence(__ATOMIC_ACQUIRE, "agent");
;             xb_add(&bar[XB_XGEN(b.x)], 1u);
;             asm volatile("s_waitcnt vmcnt(0)" ::: "memory");
;         } else {
;             XB_SPIN(xb_ld(&bar[XB_XGEN(b.x)]) == gen, bar);
;             __builtin_amdgcn_fence(__ATOMIC_ACQUIRE, "agent");
;             asm volatile("s_waitcnt vmcnt(0)" ::: "memory");
;         }
;     }
;     __syncthreads();
; }
.Lgrpbar4_g256:
	v_readlane_b32 s5, v246, 63
	s_and_b32 s2, s90, 7
	s_lshl_b32 s2, s2, 7
	s_add_u32 s2, s62, s2
	s_addc_u32 s3, s63, 0
	s_add_u32 s2, s2, 0xf000
	s_addc_u32 s3, s3, 0
	s_add_u32 s6, s62, 0xd000
	s_addc_u32 s7, s63, 0
	v_mov_b32_e32 v1, 0
	v_mov_b32_e32 v2, 1
	s_mov_b32 s4, 0
	s_waitcnt vmcnt(0) lgkmcnt(0)
	s_cmp_eq_u32 s5, 1
	s_cbranch_scc1 .Lgrpbar4_same
	buffer_wbl2 sc1
	s_waitcnt vmcnt(0)

; __device__ __forceinline__ unsigned xb_ld(unsigned* p)              { return __hip_atomic_load(p, __ATOMIC_RELAXED, __HIP_MEMORY_SCOPE_AGENT); }
; __device__ __forceinline__ unsigned xb_add(unsigned* p, unsigned v) { return __hip_atomic_fetch_add(p, v, __ATOMIC_RELAXED, __HIP_MEMORY_SCOPE_AGENT); }
; #define XB_SPIN(cond, bar) do { unsigned _sp = 0; while (cond) { __builtin_amdgcn_s_sleep(1); \
;     if ((++_sp & 255u) == 0u) { if (xb_ld(&(bar)[XB_TMO])) break; if (_sp > XB_SPIN_CAP) { atomicAdd(&(bar)[XB_TMO], 1u); break; } } } } while (0)
; __device__ __forceinline__ void xcd_barrier(const XcdBarrier& b) {
;     asm volatile("s_waitcnt vmcnt(0)" ::: "memory");
;     __syncthreads();
;     if (threadIdx.x == 0) {
;         unsigned* bar = b.bar;
;         __builtin_amdgcn_s_waitcnt(0);
;         unsigned nloc = b.st[0], nx = b.st[1];
;         if (nloc == 0u) { xcd_barrier_complete(bar, b.x, nloc, nx); b.st[0] = nloc; b.st[1] = nx; }
;         const unsigned old = xb_add(&bar[XB_XSUB(b.x)], 1u);
;         const unsigned gen = old / nloc;
;         if (old + 1u == (gen + 1u) * nloc) {
;             __builtin_amdgcn_fence(__ATOMIC_RELEASE, "agent");
;             asm volatile("s_waitcnt vmcnt(0)" ::: "memory");
;             const unsigned og = xb_add(&bar[XB_TOP], 1u);
;             const unsigned tg = og / nx;
;             if (og + 1u == (tg + 1u) * nx) xb_add(&bar[XB_TOPGEN], 1u);
;             else XB_SPIN(xb_ld(&bar[XB_TOPGEN]) == tg, bar);
;             __builtin_amdgcn_fence(__ATOMIC_ACQUIRE, "agent");
;             xb_add(&bar[XB_XGEN(b.x)], 1u);
;             asm volatile("s_waitcnt vmcnt(0)" ::: "memory");
;         } else {
;             XB_SPIN(xb_ld(&bar[XB_XGEN(b.x)]) == gen, bar);
;             __builtin_amdgcn_fence(__ATOMIC_ACQUIRE, "agent");
;             asm volatile("s_waitcnt vmcnt(0)" ::: "memory");
;         }
;     }
;     __syncthreads();
; }
.LBB0_729:
	s_waitcnt vmcnt(0)
	s_waitcnt vmcnt(0) lgkmcnt(0)
	s_barrier
	s_mov_b64 s[0:1], exec
	v_readlane_b32 s2, v247, 37
	v_readlane_b32 s3, v247, 38
	s_and_b64 s[2:3], s[0:1], s[2:3]
	s_mov_b64 exec, s[2:3]
	s_cbranch_execz .LBB0_781
	s_cmpk_eq_i32 s80, 0x100
	s_cbranch_scc1 .Lgrpbar2_g256
	buffer_wbl2 sc1
	s_add_u32 s2, s62, 0x7a00
	s_addc_u32 s3, s63, 0
	v_mov_b32_e32 v1, 0
	v_mov_b32_e32 v2, 1
	s_mov_b32 s4, 0
	s_waitcnt vmcnt(0) lgkmcnt(0)
	global_atomic_add v1, v2, s[2:3]

; __device__ __forceinline__ unsigned xb_ld(unsigned* p)              { return __hip_atomic_load(p, __ATOMIC_RELAXED, __HIP_MEMORY_SCOPE_AGENT); }
; __device__ __forceinline__ unsigned xb_add(unsigned* p, unsigned v) { return __hip_atomic_fetch_add(p, v, __ATOMIC_RELAXED, __HIP_MEMORY_SCOPE_AGENT); }
; #define XB_SPIN(cond, bar) do { unsigned _sp = 0; while (cond) { __builtin_amdgcn_s_sleep(1); \
;     if ((++_sp & 255u) == 0u) { if (xb_ld(&(bar)[XB_TMO])) break; if (_sp > XB_SPIN_CAP) { atomicAdd(&(bar)[XB_TMO], 1u); break; } } } } while (0)
; __device__ __forceinline__ void xcd_barrier(const XcdBarrier& b) {
;     asm volatile("s_waitcnt vmcnt(0)" ::: "memory");
;     __syncthreads();
;     if (threadIdx.x == 0) {
;         unsigned* bar = b.bar;
;         __builtin_amdgcn_s_waitcnt(0);
;         unsigned nloc = b.st[0], nx = b.st[1];
;         if (nloc == 0u) { xcd_barrier_complete(bar, b.x, nloc, nx); b.st[0] = nloc; b.st[1] = nx; }
;         const unsigned old = xb_add(&bar[XB_XSUB(b.x)], 1u);
;         const unsigned gen = old / nloc;
;         if (old + 1u == (gen + 1u) * nloc) {
;             __builtin_amdgcn_fence(__ATOMIC_RELEASE, "agent");
;             asm volatile("s_waitcnt vmcnt(0)" ::: "memory");
;             const unsigned og = xb_add(&bar[XB_TOP], 1u);
;             const unsigned tg = og / nx;
;             if (og + 1u == (tg + 1u) * nx) xb_add(&bar[XB_TOPGEN], 1u);
;             else XB_SPIN(xb_ld(&bar[XB_TOPGEN]) == tg, bar);
;             __builtin_amdgcn_fence(__ATOMIC_ACQUIRE, "agent");
;             xb_add(&bar[XB_XGEN(b.x)], 1u);
;             asm volatile("s_waitcnt vmcnt(0)" ::: "memory");
;         } else {
;             XB_SPIN(xb_ld(&bar[XB_XGEN(b.x)]) == gen, bar);
;             __builtin_amdgcn_fence(__ATOMIC_ACQUIRE, "agent");
;             asm volatile("s_waitcnt vmcnt(0)" ::: "memory");
;         }
;     }
;     __syncthreads();
; }
.Lgrpbar2_g256:
	v_readlane_b32 s5, v246, 62
	s_and_b32 s2, s90, 31
	s_lshl_b32 s2, s2, 6
	s_add_u32 s2, s62, s2
	s_addc_u32 s3, s63, 0
	s_add_u32 s2, s2, 0xb000
	s_addc_u32 s3, s3, 0
	s_add_u32 s6, s62, 0xc000
	s_addc_u32 s7, s63, 0
	v_mov_b32_e32 v1, 0
	v_mov_b32_e32 v2, 1
	s_mov_b32 s4, 0
	s_waitcnt vmcnt(0) lgkmcnt(0)
	s_cmp_eq_u32 s5, 1
	s_cbranch_scc1 .Lgrpbar2_same
	buffer_wbl2 sc1
	s_waitcnt vmcnt(0)

; __device__ __forceinline__ unsigned xb_ld(unsigned* p)              { return __hip_atomic_load(p, __ATOMIC_RELAXED, __HIP_MEMORY_SCOPE_AGENT); }
; __device__ __forceinline__ unsigned xb_add(unsigned* p, unsigned v) { return __hip_atomic_fetch_add(p, v, __ATOMIC_RELAXED, __HIP_MEMORY_SCOPE_AGENT); }
; #define XB_SPIN(cond, bar) do { unsigned _sp = 0; while (cond) { __builtin_amdgcn_s_sleep(1); \
;     if ((++_sp & 255u) == 0u) { if (xb_ld(&(bar)[XB_TMO])) break; if (_sp > XB_SPIN_CAP) { atomicAdd(&(bar)[XB_TMO], 1u); break; } } } } while (0)
; __device__ __forceinline__ void xcd_barrier(const XcdBarrier& b) {
;     asm volatile("s_waitcnt vmcnt(0)" ::: "memory");
;     __syncthreads();
;     if (threadIdx.x == 0) {
;         unsigned* bar = b.bar;
;         __builtin_amdgcn_s_waitcnt(0);
;         unsigned nloc = b.st[0], nx = b.st[1];
;         if (nloc == 0u) { xcd_barrier_complete(bar, b.x, nloc, nx); b.st[0] = nloc; b.st[1] = nx; }
;         const unsigned old = xb_add(&bar[XB_XSUB(b.x)], 1u);
;         const unsigned gen = old / nloc;
;         if (old + 1u == (gen + 1u) * nloc) {
;             __builtin_amdgcn_fence(__ATOMIC_RELEASE, "agent");
;             asm volatile("s_waitcnt vmcnt(0)" ::: "memory");
;             const unsigned og = xb_add(&bar[XB_TOP], 1u);
;             const unsigned tg = og / nx;
;             if (og + 1u == (tg + 1u) * nx) xb_add(&bar[XB_TOPGEN], 1u);
;             else XB_SPIN(xb_ld(&bar[XB_TOPGEN]) == tg, bar);
;             __builtin_amdgcn_fence(__ATOMIC_ACQUIRE, "agent");
;             xb_add(&bar[XB_XGEN(b.x)], 1u);
;             asm volatile("s_waitcnt vmcnt(0)" ::: "memory");
;         } else {
;             XB_SPIN(xb_ld(&bar[XB_XGEN(b.x)]) == gen, bar);
;             __builtin_amdgcn_fence(__ATOMIC_ACQUIRE, "agent");
;             asm volatile("s_waitcnt vmcnt(0)" ::: "memory");
;         }
;     }
;     __syncthreads();
; }
.LBB0_823:
	s_cmp_lt_i32 s19, 7
	s_cbranch_scc1 .LBB0_877
	s_waitcnt vmcnt(0)
	s_waitcnt vmcnt(0) lgkmcnt(0)
	s_barrier
	s_mov_b64 s[0:1], exec
	v_readlane_b32 s2, v247, 37
	v_readlane_b32 s3, v247, 38
	s_and_b64 s[2:3], s[0:1], s[2:3]
	s_mov_b64 exec, s[2:3]
	s_cbranch_execz .LBB0_876
	s_cmpk_eq_i32 s80, 0x100
	s_cbranch_scc1 .Lgrpbar1_g256
	buffer_wbl2 sc1
	s_add_u32 s2, s62, 0x7900
	s_addc_u32 s3, s63, 0
	v_mov_b32_e32 v1, 0
	v_mov_b32_e32 v2, 1
	s_mov_b32 s4, 0
	s_waitcnt vmcnt(0) lgkmcnt(0)
	global_atomic_add v1, v2, s[2:3]

; __device__ __forceinline__ unsigned xb_ld(unsigned* p)              { return __hip_atomic_load(p, __ATOMIC_RELAXED, __HIP_MEMORY_SCOPE_AGENT); }
; __device__ __forceinline__ unsigned xb_add(unsigned* p, unsigned v) { return __hip_atomic_fetch_add(p, v, __ATOMIC_RELAXED, __HIP_MEMORY_SCOPE_AGENT); }
; #define XB_SPIN(cond, bar) do { unsigned _sp = 0; while (cond) { __builtin_amdgcn_s_sleep(1); \
;     if ((++_sp & 255u) == 0u) { if (xb_ld(&(bar)[XB_TMO])) break; if (_sp > XB_SPIN_CAP) { atomicAdd(&(bar)[XB_TMO], 1u); break; } } } } while (0)
; __device__ __forceinline__ void xcd_barrier(const XcdBarrier& b) {
;     asm volatile("s_waitcnt vmcnt(0)" ::: "memory");
;     __syncthreads();
;     if (threadIdx.x == 0) {
;         unsigned* bar = b.bar;
;         __builtin_amdgcn_s_waitcnt(0);
;         unsigned nloc = b.st[0], nx = b.st[1];
;         if (nloc == 0u) { xcd_barrier_complete(bar, b.x, nloc, nx); b.st[0] = nloc; b.st[1] = nx; }
;         const unsigned old = xb_add(&bar[XB_XSUB(b.x)], 1u);
;         const unsigned gen = old / nloc;
;         if (old + 1u == (gen + 1u) * nloc) {
;             __builtin_amdgcn_fence(__ATOMIC_RELEASE, "agent");
;             asm volatile("s_waitcnt vmcnt(0)" ::: "memory");
;             const unsigned og = xb_add(&bar[XB_TOP], 1u);
;             const unsigned tg = og / nx;
;             if (og + 1u == (tg + 1u) * nx) xb_add(&bar[XB_TOPGEN], 1u);
;             else XB_SPIN(xb_ld(&bar[XB_TOPGEN]) == tg, bar);
;             __builtin_amdgcn_fence(__ATOMIC_ACQUIRE, "agent");
;             xb_add(&bar[XB_XGEN(b.x)], 1u);
;             asm volatile("s_waitcnt vmcnt(0)" ::: "memory");
;         } else {
;             XB_SPIN(xb_ld(&bar[XB_XGEN(b.x)]) == gen, bar);
;             __builtin_amdgcn_fence(__ATOMIC_ACQUIRE, "agent");
;             asm volatile("s_waitcnt vmcnt(0)" ::: "memory");
;         }
;     }
;     __syncthreads();
; }
.Lgrpbar1_g256:
	v_readlane_b32 s5, v246, 62
	s_and_b32 s2, s90, 31
	s_lshl_b32 s2, s2, 6
	s_add_u32 s2, s62, s2
	s_addc_u32 s3, s63, 0
	s_add_u32 s2, s2, 0x8000
	s_addc_u32 s3, s3, 0
	s_add_u32 s6, s62, 0xc000
	s_addc_u32 s7, s63, 0
	v_mov_b32_e32 v1, 0
	v_mov_b32_e32 v2, 1
	s_mov_b32 s4, 0
	s_waitcnt vmcnt(0) lgkmcnt(0)
	s_cmp_eq_u32 s5, 1
	s_cbranch_scc1 .Lgrpbar1_same
	buffer_wbl2 sc1
	s_waitcnt vmcnt(0)

; __device__ __forceinline__ unsigned xb_ld(unsigned* p)              { return __hip_atomic_load(p, __ATOMIC_RELAXED, __HIP_MEMORY_SCOPE_AGENT); }
; __device__ __forceinline__ unsigned xb_add(unsigned* p, unsigned v) { return __hip_atomic_fetch_add(p, v, __ATOMIC_RELAXED, __HIP_MEMORY_SCOPE_AGENT); }
; #define XB_SPIN(cond, bar) do { unsigned _sp = 0; while (cond) { __builtin_amdgcn_s_sleep(1); \
;     if ((++_sp & 255u) == 0u) { if (xb_ld(&(bar)[XB_TMO])) break; if (_sp > XB_SPIN_CAP) { atomicAdd(&(bar)[XB_TMO], 1u); break; } } } } while (0)
; __device__ __forceinline__ void xcd_barrier(const XcdBarrier& b) {
;     asm volatile("s_waitcnt vmcnt(0)" ::: "memory");
;     __syncthreads();
;     if (threadIdx.x == 0) {
;         unsigned* bar = b.bar;
;         __builtin_amdgcn_s_waitcnt(0);
;         unsigned nloc = b.st[0], nx = b.st[1];
;         if (nloc == 0u) { xcd_barrier_complete(bar, b.x, nloc, nx); b.st[0] = nloc; b.st[1] = nx; }
;         const unsigned old = xb_add(&bar[XB_XSUB(b.x)], 1u);
;         const unsigned gen = old / nloc;
;         if (old + 1u == (gen + 1u) * nloc) {
;             __builtin_amdgcn_fence(__ATOMIC_RELEASE, "agent");
;             asm volatile("s_waitcnt vmcnt(0)" ::: "memory");
;             const unsigned og = xb_add(&bar[XB_TOP], 1u);
;             const unsigned tg = og / nx;
;             if (og + 1u == (tg + 1u) * nx) xb_add(&bar[XB_TOPGEN], 1u);
;             else XB_SPIN(xb_ld(&bar[XB_TOPGEN]) == tg, bar);
;             __builtin_amdgcn_fence(__ATOMIC_ACQUIRE, "agent");
;             xb_add(&bar[XB_XGEN(b.x)], 1u);
;             asm volatile("s_waitcnt vmcnt(0)" ::: "memory");
;         } else {
;             XB_SPIN(xb_ld(&bar[XB_XGEN(b.x)]) == gen, bar);
;             __builtin_amdgcn_fence(__ATOMIC_ACQUIRE, "agent");
;             asm volatile("s_waitcnt vmcnt(0)" ::: "memory");
;         }
;     }
;     __syncthreads();
; }
.LBB0_902:
	s_cmp_lt_i32 s19, 9
	s_cbranch_scc1 .LBB0_956
	s_waitcnt vmcnt(0)
	s_waitcnt vmcnt(0) lgkmcnt(0)
	s_barrier
	s_mov_b64 s[0:1], exec
	v_readlane_b32 s2, v247, 37
	v_readlane_b32 s3, v247, 38
	s_and_b64 s[2:3], s[0:1], s[2:3]
	s_mov_b64 exec, s[2:3]
	s_cbranch_execz .LBB0_955
	s_cmpk_eq_i32 s80, 0x100
	s_cbranch_scc1 .Lgrpbar0_g256
	buffer_wbl2 sc1
	s_add_u32 s2, s62, 0x7800
	s_addc_u32 s3, s63, 0
	v_mov_b32_e32 v1, 0
	v_mov_b32_e32 v2, 1
	s_mov_b32 s4, 0
	s_waitcnt vmcnt(0) lgkmcnt(0)
	global_atomic_add v1, v2, s[2:3]

; __device__ __forceinline__ unsigned xb_ld(unsigned* p)              { return __hip_atomic_load(p, __ATOMIC_RELAXED, __HIP_MEMORY_SCOPE_AGENT); }
; __device__ __forceinline__ unsigned xb_add(unsigned* p, unsigned v) { return __hip_atomic_fetch_add(p, v, __ATOMIC_RELAXED, __HIP_MEMORY_SCOPE_AGENT); }
; #define XB_SPIN(cond, bar) do { unsigned _sp = 0; while (cond) { __builtin_amdgcn_s_sleep(1); \
;     if ((++_sp & 255u) == 0u) { if (xb_ld(&(bar)[XB_TMO])) break; if (_sp > XB_SPIN_CAP) { atomicAdd(&(bar)[XB_TMO], 1u); break; } } } } while (0)
; __device__ __forceinline__ void xcd_barrier(const XcdBarrier& b) {
;     asm volatile("s_waitcnt vmcnt(0)" ::: "memory");
;     __syncthreads();
;     if (threadIdx.x == 0) {
;         unsigned* bar = b.bar;
;         __builtin_amdgcn_s_waitcnt(0);
;         unsigned nloc = b.st[0], nx = b.st[1];
;         if (nloc == 0u) { xcd_barrier_complete(bar, b.x, nloc, nx); b.st[0] = nloc; b.st[1] = nx; }
;         const unsigned old = xb_add(&bar[XB_XSUB(b.x)], 1u);
;         const unsigned gen = old / nloc;
;         if (old + 1u == (gen + 1u) * nloc) {
;             __builtin_amdgcn_fence(__ATOMIC_RELEASE, "agent");
;             asm volatile("s_waitcnt vmcnt(0)" ::: "memory");
;             const unsigned og = xb_add(&bar[XB_TOP], 1u);
;             const unsigned tg = og / nx;
;             if (og + 1u == (tg + 1u) * nx) xb_add(&bar[XB_TOPGEN], 1u);
;             else XB_SPIN(xb_ld(&bar[XB_TOPGEN]) == tg, bar);
;             __builtin_amdgcn_fence(__ATOMIC_ACQUIRE, "agent");
;             xb_add(&bar[XB_XGEN(b.x)], 1u);
;             asm volatile("s_waitcnt vmcnt(0)" ::: "memory");
;         } else {
;             XB_SPIN(xb_ld(&bar[XB_XGEN(b.x)]) == gen, bar);
;             __builtin_amdgcn_fence(__ATOMIC_ACQUIRE, "agent");
;             asm volatile("s_waitcnt vmcnt(0)" ::: "memory");
;         }
;     }
;     __syncthreads();
; }
.Lgrpbar0_g256:
	v_readlane_b32 s5, v246, 62
	s_and_b32 s2, s90, 31
	s_lshl_b32 s2, s2, 6
	s_add_u32 s2, s62, s2
	s_addc_u32 s3, s63, 0
	s_add_u32 s2, s2, 0x9000
	s_addc_u32 s3, s3, 0
	s_add_u32 s6, s62, 0xc000
	s_addc_u32 s7, s63, 0
	v_mov_b32_e32 v1, 0
	v_mov_b32_e32 v2, 1
	s_mov_b32 s4, 0
	s_waitcnt vmcnt(0) lgkmcnt(0)
	s_cmp_eq_u32 s5, 1
	s_cbranch_scc1 .Lgrpbar0_same
	buffer_wbl2 sc1
	s_waitcnt vmcnt(0)
